# v32 + nt on the two remaining single-touch z-row loads in the NSA write-out
# speedup vs baseline: 1.0090x; 1.0082x over previous
; DI void write_out_zh(const f32x16& o0, const f32x16& o1, float sc, const u32x4 (&zpre)[2], const bf16* zrow0, size_t zpitch, bf16* orow0, size_t opitch, float* st, int lane) {
;     const int q = lane & 31, hi = lane >> 5;
; #pragma unroll
;     for (int d0 = 0; d0 < 2; ++d0)
; #pragma unroll
;         for (int gq = 0; gq < 4; ++gq) {
;             const int ch = 8 * d0 + 2 * gq + hi; const f32x16& o = d0 ? o1 : o0;
;             *(f32x4*)(st + q * 64 + ((ch ^ (q & 15)) << 2)) = (f32x4){o[4 * gq] * sc, o[4 * gq + 1] * sc, o[4 * gq + 2] * sc, o[4 * gq + 3] * sc};
;         }
; #pragma unroll
;     for (int j = 0; j < 4; ++j) {
;         const int row = (lane >> 3) + 8 * j, c = lane & 7;
;         const f32x4 a = *(const f32x4*)(st + row * 64 + (((2 * c) ^ (row & 15)) << 2)), b = *(const f32x4*)(st + row * 64 + (((2 * c + 1) ^ (row & 15)) << 2));
;         const u32x4 zz = j < 2 ? zpre[j & 1] : *(const u32x4*)(zrow0 + (size_t)row * zpitch + 8 * c);
; DI void nsa_unit(const bf16* PR, const float* AUX, const bf16* KC, const bf16* VC, bf16* MIX, char* sm, int b, int qb) {
;     ...
;         const float lt = l + __shfl_xor(l, 32); const float sc = lt > 0.f ? g2 / lt : 0.f;
; #pragma unroll
;         for (int i = 0; i < 16; ++i) { o0[i] = tacc[i * 64] + sc * o0[i]; o1[i] = tacc[(16 + i) * 64] + sc * o1[i]; }
.LBB0_548:
	v_mul_f32_e32 v0, 0xbfb8aa3b, v140
	v_exp_f32_e32 v0, v0
	ds_bpermute_b32 v2, v212, v223
	v_add_f32_e32 v0, 1.0, v0
	v_rcp_f32_e32 v0, v0
	s_waitcnt lgkmcnt(0)
	v_add_f32_e32 v38, v223, v2
	ds_read2st64_b32 v[2:3], v217 offset1:1
	ds_read2st64_b32 v[36:37], v217 offset0:2 offset1:3
	v_div_scale_f32 v39, s[0:1], v38, v38, v0
	s_waitcnt vmcnt(2)
	v_rcp_f32_e32 v40, v39
	v_div_scale_f32 v41, vcc, v0, v38, v0
	s_lshl_b64 s[0:1], s[8:9], 11
	v_fma_f32 v42, -v39, v40, 1.0
	v_fmac_f32_e32 v40, v42, v40
	v_mul_f32_e32 v42, v41, v40
	v_fma_f32 v43, -v39, v42, v41
	v_fmac_f32_e32 v42, v43, v40
	v_fma_f32 v39, -v39, v42, v41
	v_div_fmas_f32 v39, v39, v40, v42
	v_div_fixup_f32 v0, v39, v38, v0
	v_cmp_lt_f32_e32 vcc, 0, v38
	ds_read2st64_b32 v[38:39], v217 offset0:16 offset1:17
	ds_read2st64_b32 v[40:41], v217 offset0:18 offset1:19
	ds_read2st64_b32 v[42:43], v217 offset0:4 offset1:5
	ds_read2st64_b32 v[44:45], v217 offset0:6 offset1:7
	v_cndmask_b32_e32 v0, 0, v0, vcc
	s_waitcnt lgkmcnt(4)
	v_pk_fma_f32 v[22:23], v[22:23], v[0:1], v[36:37] op_sel_hi:[1,0,1]
	ds_read2st64_b32 v[36:37], v217 offset0:20 offset1:21
	ds_read2st64_b32 v[46:47], v217 offset0:22 offset1:23
	v_pk_fma_f32 v[20:21], v[20:21], v[0:1], v[2:3] op_sel_hi:[1,0,1]
	s_waitcnt lgkmcnt(5)
	v_pk_fma_f32 v[2:3], v[4:5], v[0:1], v[38:39] op_sel_hi:[1,0,1]
	s_waitcnt lgkmcnt(4)
	v_pk_fma_f32 v[4:5], v[6:7], v[0:1], v[40:41] op_sel_hi:[1,0,1]
	s_waitcnt lgkmcnt(3)
	v_pk_fma_f32 v[6:7], v[24:25], v[0:1], v[42:43] op_sel_hi:[1,0,1]
	s_waitcnt lgkmcnt(1)
	v_pk_fma_f32 v[24:25], v[8:9], v[0:1], v[36:37] op_sel_hi:[1,0,1]
	v_pk_fma_f32 v[8:9], v[26:27], v[0:1], v[44:45] op_sel_hi:[1,0,1]
	s_waitcnt lgkmcnt(0)
	v_pk_fma_f32 v[26:27], v[10:11], v[0:1], v[46:47] op_sel_hi:[1,0,1]
	ds_read2st64_b32 v[10:11], v217 offset0:8 offset1:9
	ds_read2st64_b32 v[36:37], v217 offset0:24 offset1:25
	ds_read2st64_b32 v[38:39], v217 offset0:10 offset1:11
	ds_read2st64_b32 v[40:41], v217 offset0:12 offset1:13
	ds_read2st64_b32 v[42:43], v217 offset0:14 offset1:15
	ds_read2st64_b32 v[44:45], v217 offset0:26 offset1:27
	ds_read2st64_b32 v[46:47], v217 offset0:28 offset1:29
	ds_read2st64_b32 v[48:49], v217 offset0:30 offset1:31
	s_waitcnt lgkmcnt(7)
	v_pk_fma_f32 v[10:11], v[28:29], v[0:1], v[10:11] op_sel_hi:[1,0,1]
	s_waitcnt lgkmcnt(6)
	v_pk_fma_f32 v[28:29], v[12:13], v[0:1], v[36:37] op_sel_hi:[1,0,1]
	s_waitcnt lgkmcnt(5)
	v_pk_fma_f32 v[12:13], v[30:31], v[0:1], v[38:39] op_sel_hi:[1,0,1]
	s_waitcnt lgkmcnt(2)
	v_pk_fma_f32 v[30:31], v[14:15], v[0:1], v[44:45] op_sel_hi:[1,0,1]
	v_pk_fma_f32 v[14:15], v[32:33], v[0:1], v[40:41] op_sel_hi:[1,0,1]
	s_waitcnt lgkmcnt(1)
	v_pk_fma_f32 v[32:33], v[16:17], v[0:1], v[46:47] op_sel_hi:[1,0,1]
	v_pk_fma_f32 v[16:17], v[34:35], v[0:1], v[42:43] op_sel_hi:[1,0,1]
	s_waitcnt lgkmcnt(0)
	v_pk_fma_f32 v[34:35], v[18:19], v[0:1], v[48:49] op_sel_hi:[1,0,1]
	v_and_b32_e32 v0, 0x7c0, v162
	v_lshl_add_u32 v0, v0, 2, s16
	v_bitop3_b32 v19, v160, v161, 15 bitop3:0x78
	v_and_b32_e32 v18, 15, v161
	v_lshl_add_u32 v19, v19, 4, v0
	ds_write_b128 v19, v[20:23]
	v_bitop3_b32 v19, v160, v18, 2 bitop3:0x36
	v_lshl_add_u32 v19, v19, 4, v0
	ds_write_b128 v19, v[6:9]
	v_bitop3_b32 v6, v160, v18, 4 bitop3:0x36
	v_lshl_add_u32 v6, v6, 4, v0
	ds_write_b128 v6, v[10:13]
	v_bitop3_b32 v6, v160, v18, 6 bitop3:0x36
	v_lshl_add_u32 v6, v6, 4, v0
	ds_write_b128 v6, v[14:17]
	v_bitop3_b32 v6, v160, v18, 8 bitop3:0x36
	v_lshl_add_u32 v6, v6, 4, v0
	ds_write_b128 v6, v[2:5]
	v_bitop3_b32 v2, v160, v18, 10 bitop3:0x36
	v_lshl_add_u32 v2, v2, 4, v0
	ds_write_b128 v2, v[24:27]
	v_bitop3_b32 v2, v160, v18, 12 bitop3:0x36
	v_lshl_add_u32 v2, v2, 4, v0
	ds_write_b128 v2, v[28:31]
	v_bitop3_b32 v2, v160, v18, 14 bitop3:0x36
	v_lshrrev_b32_e32 v30, 3, v149
	v_lshlrev_b32_e32 v31, 1, v218
	s_add_u32 s0, s96, s0
	v_lshl_add_u32 v0, v2, 4, v0
	v_bitop3_b32 v7, v31, v30, 1 bitop3:0x36
	v_lshlrev_b32_e32 v14, 16, v104
	s_addc_u32 s1, s97, s1
	ds_write_b128 v0, v[32:35]
	v_lshlrev_b32_e32 v34, 4, v7
	v_and_b32_e32 v15, 0xffff0000, v104
	v_mul_f32_e32 v7, 0xbfb8aa3b, v14
	s_add_u32 s0, s0, s14
	v_exp_f32_e32 v16, v7
	v_mul_f32_e32 v7, 0xbfb8aa3b, v15
	s_addc_u32 s1, s1, s15
	v_lshlrev_b32_e32 v0, 4, v218
	v_xor_b32_e32 v6, v30, v31
	v_exp_f32_e32 v17, v7
	v_lshl_add_u64 v[2:3], s[0:1], 0, v[0:1]
	v_lshl_add_u64 v[4:5], s[4:5], 0, v[0:1]
	v_lshl_add_u32 v0, v30, 8, s16
	v_lshlrev_b32_e32 v33, 4, v6
	v_add_u32_e32 v6, v0, v33
	v_add_u32_e32 v0, v0, v34
	ds_read_b128 v[6:9], v6
	ds_read_b128 v[10:13], v0
	v_add_f32_e32 v0, 1.0, v16
	v_lshlrev_b32_e32 v18, 16, v105
	v_rcp_f32_e32 v16, v0
	v_add_f32_e32 v0, 1.0, v17
	v_and_b32_e32 v19, 0xffff0000, v105
	v_mul_f32_e32 v17, 0xbfb8aa3b, v18
	v_exp_f32_e32 v20, v17
	v_mul_f32_e32 v17, 0xbfb8aa3b, v19
	v_exp_f32_e32 v21, v17
	v_rcp_f32_e32 v17, v0
	v_add_f32_e32 v0, 1.0, v20
	v_rcp_f32_e32 v20, v0
	v_add_f32_e32 v0, 1.0, v21
	v_rcp_f32_e32 v21, v0
	v_pk_mul_f32 v[14:15], v[16:17], v[14:15]
	v_or_b32_e32 v28, 8, v30
	s_waitcnt lgkmcnt(1)
	v_pk_mul_f32 v[6:7], v[14:15], v[6:7]
	v_pk_mul_f32 v[14:15], v[20:21], v[18:19]
	v_lshlrev_b32_e32 v18, 16, v106
	v_mul_f32_e32 v0, 0xbfb8aa3b, v18
	v_exp_f32_e32 v0, v0
	v_pk_mul_f32 v[8:9], v[14:15], v[8:9]
	v_and_b32_e32 v19, 0xffff0000, v106
	v_cvt_pk_bf16_f32 v6, v6, v7
	v_add_f32_e32 v0, 1.0, v0
	v_cvt_pk_bf16_f32 v7, v8, v9
	v_rcp_f32_e32 v8, v0
	v_mul_f32_e32 v0, 0xbfb8aa3b, v19
	v_exp_f32_e32 v0, v0
	v_lshlrev_b32_e32 v20, 16, v107
	v_mul_f32_e32 v9, 0xbfb8aa3b, v20
	v_and_b32_e32 v21, 0xffff0000, v107
	v_add_f32_e32 v0, 1.0, v0
	v_exp_f32_e32 v14, v9
	v_rcp_f32_e32 v9, v0
	v_mul_f32_e32 v0, 0xbfb8aa3b, v21
	v_exp_f32_e32 v27, v0
	v_lshlrev_b32_e32 v0, 11, v30
	v_lshl_add_u64 v[22:23], v[2:3], 0, v[0:1]
	v_lshlrev_b32_e32 v0, 11, v28
	v_or_b32_e32 v35, 16, v30
	v_lshl_add_u64 v[24:25], v[2:3], 0, v[0:1]
	v_lshlrev_b32_e32 v0, 13, v35
	v_add_f32_e32 v26, 1.0, v14
	v_lshl_add_u64 v[14:15], v[4:5], 0, v[0:1]
	global_load_dwordx4 v[14:17], v[14:15], off nt
	v_add_f32_e32 v0, 1.0, v27
	v_rcp_f32_e32 v26, v26
	v_rcp_f32_e32 v27, v0
	v_pk_mul_f32 v[8:9], v[8:9], v[18:19]
	v_or_b32_e32 v32, 1, v31
	s_waitcnt lgkmcnt(0)
; #define LAS __attribute__((address_space(3)))
; DI float bf2f(unsigned h) { return __uint_as_float(h << 16); }
; DI unsigned cvtpk(float lo, float hi) { f32x2_t v = {lo, hi}; bf16x2_t b = __builtin_convertvector(v, bf16x2_t); return __builtin_bit_cast(unsigned, b); }
; DI float silu_f(float z) { return z * sigm_f(z); }
; DI void write_out_zh(const f32x16& o0, const f32x16& o1, float sc, const u32x4 (&zpre)[2], const bf16* zrow0, size_t zpitch, bf16* orow0, size_t opitch, float* st, int lane) {
;     ...
; #pragma unroll
;     for (int j = 0; j < 4; ++j) {
;         const int row = (lane >> 3) + 8 * j, c = lane & 7;
;         const f32x4 a = *(const f32x4*)(st + row * 64 + (((2 * c) ^ (row & 15)) << 2)), b = *(const f32x4*)(st + row * 64 + (((2 * c + 1) ^ (row & 15)) << 2));
;         const u32x4 zz = j < 2 ? zpre[j & 1] : *(const u32x4*)(zrow0 + (size_t)row * zpitch + 8 * c);
;         u32x4 w;
;         w.x = cvtpk(a[0] * silu_f(bf2f(zz.x & 0xffffu)), a[1] * silu_f(bf2f(zz.x >> 16)));
;         w.y = cvtpk(a[2] * silu_f(bf2f(zz.y & 0xffffu)), a[3] * silu_f(bf2f(zz.y >> 16)));
;         w.z = cvtpk(b[0] * silu_f(bf2f(zz.z & 0xffffu)), b[1] * silu_f(bf2f(zz.z >> 16)));
;         w.w = cvtpk(b[2] * silu_f(bf2f(zz.w & 0xffffu)), b[3] * silu_f(bf2f(zz.w >> 16)));
;         *(u32x4*)(orow0 + (size_t)row * opitch + 8 * c) = w;
;     }
; __global__ void __launch_bounds__(512, 2) mega_fwd(Params p) {
;     ...
;             { volatile LAS int* slot = (volatile LAS int*)(sm + L_MISC); __syncthreads(); if (threadIdx.x == 0) *slot = nxt_; __syncthreads(); u = *slot; }
	v_pk_mul_f32 v[8:9], v[8:9], v[10:11]
	v_pk_mul_f32 v[10:11], v[26:27], v[20:21]
	v_cvt_pk_bf16_f32 v8, v8, v9
	v_pk_mul_f32 v[10:11], v[10:11], v[12:13]
	v_lshl_add_u32 v0, v28, 8, s16
	v_cvt_pk_bf16_f32 v9, v10, v11
	global_store_dwordx4 v[22:23], v[6:9], off offset:1536
	v_lshlrev_b32_e32 v18, 16, v100
	v_and_b32_e32 v19, 0xffff0000, v100
	v_bitop3_b32 v6, v30, v31, 8 bitop3:0x36
	v_bitop3_b32 v7, v30, v32, 8 bitop3:0x36
	v_lshl_add_u32 v6, v6, 4, v0
	v_lshl_add_u32 v0, v7, 4, v0
	v_mul_f32_e32 v7, 0xbfb8aa3b, v18
	v_exp_f32_e32 v20, v7
	v_mul_f32_e32 v7, 0xbfb8aa3b, v19
	v_exp_f32_e32 v21, v7
	ds_read_b128 v[6:9], v6
	ds_read_b128 v[10:13], v0
	v_add_f32_e32 v0, 1.0, v20
	v_lshlrev_b32_e32 v22, 16, v101
	v_rcp_f32_e32 v20, v0
	v_add_f32_e32 v0, 1.0, v21
	v_and_b32_e32 v23, 0xffff0000, v101
	v_mul_f32_e32 v21, 0xbfb8aa3b, v22
	v_exp_f32_e32 v26, v21
	v_mul_f32_e32 v21, 0xbfb8aa3b, v23
	v_exp_f32_e32 v27, v21
	v_rcp_f32_e32 v21, v0
	v_add_f32_e32 v0, 1.0, v26
	v_rcp_f32_e32 v26, v0
	v_add_f32_e32 v0, 1.0, v27
	v_rcp_f32_e32 v27, v0
	v_pk_mul_f32 v[18:19], v[20:21], v[18:19]
	v_or_b32_e32 v30, 24, v30
	s_waitcnt lgkmcnt(1)
	v_pk_mul_f32 v[6:7], v[18:19], v[6:7]
	v_pk_mul_f32 v[18:19], v[26:27], v[22:23]
	v_lshlrev_b32_e32 v22, 16, v102
	v_mul_f32_e32 v0, 0xbfb8aa3b, v22
	v_exp_f32_e32 v0, v0
	v_and_b32_e32 v23, 0xffff0000, v102
	v_cvt_pk_bf16_f32 v6, v6, v7
	v_mul_f32_e32 v7, 0xbfb8aa3b, v23
	v_pk_mul_f32 v[8:9], v[18:19], v[8:9]
	v_exp_f32_e32 v18, v7
	v_add_f32_e32 v0, 1.0, v0
	v_cvt_pk_bf16_f32 v7, v8, v9
	v_rcp_f32_e32 v8, v0
	v_lshlrev_b32_e32 v0, 11, v35
	v_lshl_add_u64 v[28:29], v[2:3], 0, v[0:1]
	v_lshlrev_b32_e32 v0, 13, v30
	v_lshl_add_u64 v[4:5], v[4:5], 0, v[0:1]
	v_add_f32_e32 v9, 1.0, v18
	global_load_dwordx4 v[18:21], v[4:5], off nt
	v_lshlrev_b32_e32 v26, 16, v103
	v_and_b32_e32 v27, 0xffff0000, v103
	v_mul_f32_e32 v0, 0xbfb8aa3b, v26
	v_exp_f32_e32 v0, v0
	v_mul_f32_e32 v4, 0xbfb8aa3b, v27
	v_exp_f32_e32 v5, v4
	v_rcp_f32_e32 v9, v9
	v_add_f32_e32 v0, 1.0, v0
	v_rcp_f32_e32 v4, v0
	v_add_f32_e32 v0, 1.0, v5
	v_rcp_f32_e32 v5, v0
	v_pk_mul_f32 v[8:9], v[8:9], v[22:23]
	v_lshl_add_u32 v0, v35, 8, s16
	s_waitcnt lgkmcnt(0)
	v_pk_mul_f32 v[8:9], v[8:9], v[10:11]
	v_pk_mul_f32 v[4:5], v[4:5], v[26:27]
	v_cvt_pk_bf16_f32 v8, v8, v9
	v_pk_mul_f32 v[4:5], v[4:5], v[12:13]
	s_waitcnt vmcnt(2)
	v_lshlrev_b32_e32 v12, 16, v14
	v_cvt_pk_bf16_f32 v9, v4, v5
	v_and_b32_e32 v13, 0xffff0000, v14
	v_mul_f32_e32 v5, 0xbfb8aa3b, v12
	v_exp_f32_e32 v14, v5
	v_mul_f32_e32 v5, 0xbfb8aa3b, v13
	v_exp_f32_e32 v22, v5
	global_store_dwordx4 v[24:25], v[6:9], off offset:1536
	v_add_u32_e32 v4, v0, v33
	v_add_u32_e32 v0, v0, v34
	ds_read_b128 v[4:7], v4
	ds_read_b128 v[8:11], v0
	v_add_f32_e32 v0, 1.0, v14
	v_rcp_f32_e32 v14, v0
	v_add_f32_e32 v0, 1.0, v22
	v_lshlrev_b32_e32 v22, 16, v15
	v_and_b32_e32 v23, 0xffff0000, v15
	v_mul_f32_e32 v15, 0xbfb8aa3b, v22
	v_exp_f32_e32 v24, v15
	v_mul_f32_e32 v15, 0xbfb8aa3b, v23
	v_exp_f32_e32 v25, v15
	v_rcp_f32_e32 v15, v0
	v_add_f32_e32 v0, 1.0, v24
	v_rcp_f32_e32 v24, v0
	v_add_f32_e32 v0, 1.0, v25
	v_rcp_f32_e32 v25, v0
	v_pk_mul_f32 v[12:13], v[14:15], v[12:13]
	v_and_b32_e32 v15, 0xffff0000, v17
	s_waitcnt lgkmcnt(1)
	v_pk_mul_f32 v[4:5], v[4:5], v[12:13]
	v_pk_mul_f32 v[12:13], v[24:25], v[22:23]
	v_cvt_pk_bf16_f32 v4, v4, v5
	v_pk_mul_f32 v[6:7], v[6:7], v[12:13]
	v_lshlrev_b32_e32 v12, 16, v16
	v_and_b32_e32 v13, 0xffff0000, v16
	v_mul_f32_e32 v0, 0xbfb8aa3b, v12
	v_exp_f32_e32 v0, v0
	v_mul_f32_e32 v5, 0xbfb8aa3b, v13
	v_exp_f32_e32 v14, v5
	v_cvt_pk_bf16_f32 v5, v6, v7
	v_add_f32_e32 v0, 1.0, v0
	v_rcp_f32_e32 v6, v0
	v_add_f32_e32 v0, 1.0, v14
	v_lshlrev_b32_e32 v14, 16, v17
	v_mul_f32_e32 v7, 0xbfb8aa3b, v14
	v_exp_f32_e32 v16, v7
	v_mul_f32_e32 v7, 0xbfb8aa3b, v15
	v_exp_f32_e32 v17, v7
	v_rcp_f32_e32 v7, v0
	v_add_f32_e32 v0, 1.0, v16
	v_rcp_f32_e32 v16, v0
	v_add_f32_e32 v0, 1.0, v17
	v_rcp_f32_e32 v17, v0
	v_pk_mul_f32 v[6:7], v[6:7], v[12:13]
	v_lshl_add_u32 v0, v30, 8, s16
	s_waitcnt lgkmcnt(0)
	v_pk_mul_f32 v[6:7], v[8:9], v[6:7]
	v_pk_mul_f32 v[8:9], v[16:17], v[14:15]
	v_cvt_pk_bf16_f32 v6, v6, v7
	v_pk_mul_f32 v[8:9], v[10:11], v[8:9]
	s_waitcnt vmcnt(1)
	v_lshlrev_b32_e32 v12, 16, v18
	v_cvt_pk_bf16_f32 v7, v8, v9
	global_store_dwordx4 v[28:29], v[4:7], off offset:1536
	v_and_b32_e32 v13, 0xffff0000, v18
	v_lshlrev_b32_e32 v16, 16, v19
	v_bitop3_b32 v4, v30, v31, 15 bitop3:0x6c
	v_bitop3_b32 v5, v30, v32, 15 bitop3:0x6c
	v_lshl_add_u32 v4, v4, 4, v0
	v_lshl_add_u32 v0, v5, 4, v0
	v_mul_f32_e32 v5, 0xbfb8aa3b, v12
	v_exp_f32_e32 v14, v5
	v_mul_f32_e32 v5, 0xbfb8aa3b, v13
	v_exp_f32_e32 v15, v5
	ds_read_b128 v[4:7], v4
	ds_read_b128 v[8:11], v0
	v_add_f32_e32 v0, 1.0, v14
	v_rcp_f32_e32 v14, v0
	v_add_f32_e32 v0, 1.0, v15
	v_and_b32_e32 v17, 0xffff0000, v19
	v_mul_f32_e32 v15, 0xbfb8aa3b, v16
	v_exp_f32_e32 v18, v15
	v_mul_f32_e32 v15, 0xbfb8aa3b, v17
	v_exp_f32_e32 v19, v15
	v_rcp_f32_e32 v15, v0
	v_add_f32_e32 v0, 1.0, v18
	v_rcp_f32_e32 v18, v0
	v_add_f32_e32 v0, 1.0, v19
	v_rcp_f32_e32 v19, v0
	v_pk_mul_f32 v[12:13], v[14:15], v[12:13]
	v_and_b32_e32 v15, 0xffff0000, v21
	s_waitcnt lgkmcnt(1)
	v_pk_mul_f32 v[4:5], v[4:5], v[12:13]
	v_pk_mul_f32 v[12:13], v[18:19], v[16:17]
	v_cvt_pk_bf16_f32 v4, v4, v5
	v_pk_mul_f32 v[6:7], v[6:7], v[12:13]
	v_lshlrev_b32_e32 v12, 16, v20
	v_and_b32_e32 v13, 0xffff0000, v20
	v_mul_f32_e32 v0, 0xbfb8aa3b, v12
	v_exp_f32_e32 v0, v0
	v_mul_f32_e32 v5, 0xbfb8aa3b, v13
	v_exp_f32_e32 v14, v5
	v_cvt_pk_bf16_f32 v5, v6, v7
	v_add_f32_e32 v0, 1.0, v0
	v_rcp_f32_e32 v6, v0
	v_add_f32_e32 v0, 1.0, v14
	v_lshlrev_b32_e32 v14, 16, v21
	v_mul_f32_e32 v7, 0xbfb8aa3b, v14
	v_exp_f32_e32 v16, v7
	v_mul_f32_e32 v7, 0xbfb8aa3b, v15
	v_exp_f32_e32 v17, v7
	v_rcp_f32_e32 v7, v0
	v_add_f32_e32 v0, 1.0, v16
	v_rcp_f32_e32 v16, v0
	v_add_f32_e32 v0, 1.0, v17
	v_rcp_f32_e32 v17, v0
	v_pk_mul_f32 v[6:7], v[6:7], v[12:13]
	v_lshlrev_b32_e32 v0, 11, v30
	s_waitcnt lgkmcnt(0)
	v_pk_mul_f32 v[6:7], v[8:9], v[6:7]
	v_pk_mul_f32 v[8:9], v[16:17], v[14:15]
	v_cvt_pk_bf16_f32 v6, v6, v7
	v_pk_mul_f32 v[8:9], v[10:11], v[8:9]
	v_lshl_add_u64 v[2:3], v[2:3], 0, v[0:1]
	v_cvt_pk_bf16_f32 v7, v8, v9
	global_store_dwordx4 v[2:3], v[4:7], off offset:1536
	s_barrier
	s_and_saveexec_b64 s[0:1], s[72:73]
	s_waitcnt vmcnt(4)
	v_mov_b32_e32 v0, s99
	v_mov_b32_e32 v141, v252
	ds_write_b32 v0, v141
